# poll-period trim: s_sleep 1 removed from the 14 barrier generation-word spin loops (back-to-back sc1 polls); otherwise v061
# speedup vs baseline: 1.0010x; 1.0010x over previous
.LBB0_178:
	s_and_b32 s1, s0, 0xff
	s_mov_b64 s[12:13], -1
	s_cmp_lg_u32 s1, 0
	s_mov_b64 s[36:37], -1
	s_cbranch_scc0 .LBB0_181
	s_and_b64 vcc, exec, s[36:37]
	s_cbranch_vccz .LBB0_177

; DI unsigned xb_ld(unsigned* p)              { return __hip_atomic_load(p, __ATOMIC_RELAXED, __HIP_MEMORY_SCOPE_AGENT); }
; #define XB_SPIN(cond, bar) do { unsigned _sp = 0; while (cond) { __builtin_amdgcn_s_sleep(1); \
;     if ((++_sp & 255u) == 0u) { if (xb_ld(&(bar)[XB_TMO])) break; if (_sp > XB_SPIN_CAP) { atomicAdd(&(bar)[XB_TMO], 1u); break; } } } } while (0)
; DI void xcd_barrier(const XcdBarrier& b) {
;     ...
;             else XB_SPIN(xb_ld(&bar[XB_TOPGEN]) == tg, bar);
.LBB0_195:
	s_and_b32 s1, s0, 0xff
	s_mov_b64 s[14:15], -1
	s_cmp_lg_u32 s1, 0
	s_mov_b64 s[38:39], -1
	s_cbranch_scc0 .LBB0_198
	s_and_b64 vcc, exec, s[38:39]
	s_cbranch_vccz .LBB0_194
